# EpiResid: second-half residual loads issued progressively during first half (no store-drain wait)
# baseline (speedup 1.0000x reference)
.LBB0_1015:
	s_or_b64 exec, exec, s[50:51]
	s_mov_b64 s[98:99], 0x80000
	v_lshl_add_u64 v[240:241], v[200:201], 0, s[98:99]
	global_load_dwordx4 v[218:221], v[240:241], off
	global_load_dwordx4 v[222:225], v[240:241], off offset:16
	global_load_dwordx4 v[226:229], v[240:241], off offset:512
	global_load_dwordx4 v[230:233], v[240:241], off offset:528
	v_or_b32_e32 v112, 16, v198
	s_waitcnt lgkmcnt(0)
	v_ashrrev_i32_e32 v113, 31, v112
	v_lshlrev_b64 v[116:117], 10, v[112:113]
	v_readlane_b32 s64, v250, 0
	v_lshl_add_u64 v[120:121], v[116:117], 0, s[36:37]
	v_readlane_b32 s70, v250, 6
	v_readlane_b32 s71, v250, 7
	v_pk_fma_f32 v[110:111], s[48:49], v[110:111], v[174:175]
	v_pk_fma_f32 v[108:109], s[12:13], v[108:109], v[172:173]
	v_lshl_add_u64 v[116:117], v[120:121], 2, s[70:71]
	v_lshl_add_u64 v[122:123], v[196:197], 2, v[116:117]
	v_pk_fma_f32 v[106:107], s[48:49], v[106:107], v[170:171]
	v_pk_fma_f32 v[104:105], s[12:13], v[104:105], v[168:169]
	global_store_dwordx4 v[122:123], v[108:111], off
	global_store_dwordx4 v[122:123], v[104:107], off offset:16
	v_cvt_pk_bf16_f32 v116, v108, v109
	v_cvt_pk_bf16_f32 v117, v110, v111
	v_cvt_pk_bf16_f32 v118, v104, v105
	v_pk_fma_f32 v[102:103], s[48:49], v[102:103], v[166:167]
	v_mul_f32_e32 v109, v109, v109
	v_fmac_f32_e32 v109, v108, v108
	v_mul_f32_e32 v108, v111, v111
	v_fmac_f32_e32 v108, v110, v110
	v_mul_f32_e32 v105, v105, v105
	v_add_f32_e32 v108, v109, v108
	v_fmac_f32_e32 v105, v104, v104
	v_add_f32_e32 v104, v105, v108
	v_mul_f32_e32 v105, v107, v107
	v_fmac_f32_e32 v105, v106, v106
	v_pk_fma_f32 v[100:101], s[12:13], v[100:101], v[164:165]
	v_add_f32_e32 v108, v105, v104
	v_pk_fma_f32 v[104:105], s[12:13], v[96:97], v[160:161]
	v_mul_f32_e32 v96, v101, v101
	v_mul_f32_e32 v97, v103, v103
	v_fmac_f32_e32 v96, v100, v100
	v_fmac_f32_e32 v97, v102, v102
	v_add_f32_e32 v96, v96, v97
	v_mul_f32_e32 v97, v105, v105
	v_cvt_pk_bf16_f32 v119, v106, v107
	v_pk_fma_f32 v[106:107], s[48:49], v[98:99], v[162:163]
	v_fmac_f32_e32 v97, v104, v104
	v_add_f32_e32 v96, v97, v96
	v_mul_f32_e32 v97, v107, v107
	v_fmac_f32_e32 v97, v106, v106
	v_add_f32_e32 v96, v97, v96
	v_add_f32_e32 v96, v108, v96
	ds_bpermute_b32 v97, v114, v96
	v_readlane_b32 s50, v250, 42
	v_readlane_b32 s51, v250, 43
	v_readlane_b32 s65, v250, 1
	v_readlane_b32 s66, v250, 2
	s_waitcnt lgkmcnt(0)
	v_add_f32_e32 v96, v96, v97
	ds_bpermute_b32 v97, v115, v96
	v_lshl_add_u64 v[120:121], v[120:121], 1, s[50:51]
	v_lshl_add_u64 v[120:121], v[196:197], 1, v[120:121]
	v_readlane_b32 s67, v250, 3
	v_readlane_b32 s68, v250, 4
	v_readlane_b32 s69, v250, 5
	global_store_dwordx4 v[120:121], v[116:119], off
	global_store_dwordx4 v[122:123], v[100:103], off offset:512
	global_store_dwordx4 v[122:123], v[104:107], off offset:528
	v_cvt_pk_bf16_f32 v98, v100, v101
	v_cvt_pk_bf16_f32 v99, v102, v103
	s_nop 0
	v_cvt_pk_bf16_f32 v100, v104, v105
	v_cvt_pk_bf16_f32 v101, v106, v107
	global_store_dwordx4 v[120:121], v[98:101], off offset:256
	s_and_saveexec_b64 s[50:51], s[6:7]
	s_cbranch_execz .LBB0_1017
	s_lshl_b32 s53, s52, 2
	s_add_i32 s53, s53, 0
	v_lshl_add_u32 v98, v112, 4, s53
	v_add_u32_e32 v98, 0x20000, v98
	s_waitcnt lgkmcnt(0)
	v_add_f32_e32 v96, v96, v97
	ds_write_b32 v98, v96
.LBB0_1017:
	s_or_b64 exec, exec, s[50:51]
	s_mov_b64 s[98:99], 0x90000
	v_lshl_add_u64 v[240:241], v[200:201], 0, s[98:99]
	global_load_dwordx4 v[172:175], v[240:241], off
	global_load_dwordx4 v[168:171], v[240:241], off offset:16
	global_load_dwordx4 v[164:167], v[240:241], off offset:512
	global_load_dwordx4 v[160:163], v[240:241], off offset:528
	v_or_b32_e32 v96, 32, v198
	s_waitcnt lgkmcnt(0)
	v_ashrrev_i32_e32 v97, 31, v96
	v_lshlrev_b64 v[98:99], 10, v[96:97]
	v_readlane_b32 s64, v250, 0
	v_lshl_add_u64 v[102:103], v[98:99], 0, s[36:37]
	v_readlane_b32 s70, v250, 6
	v_readlane_b32 s71, v250, 7
	v_pk_fma_f32 v[94:95], s[48:49], v[94:95], v[158:159]
	v_pk_fma_f32 v[92:93], s[12:13], v[92:93], v[156:157]
	v_lshl_add_u64 v[98:99], v[102:103], 2, s[70:71]
	v_lshl_add_u64 v[104:105], v[196:197], 2, v[98:99]
	v_pk_fma_f32 v[90:91], s[48:49], v[90:91], v[154:155]
	v_pk_fma_f32 v[88:89], s[12:13], v[88:89], v[152:153]
	global_store_dwordx4 v[104:105], v[92:95], off
	global_store_dwordx4 v[104:105], v[88:91], off offset:16
	v_cvt_pk_bf16_f32 v98, v92, v93
	v_cvt_pk_bf16_f32 v99, v94, v95
	v_cvt_pk_bf16_f32 v100, v88, v89
	v_pk_fma_f32 v[86:87], s[48:49], v[86:87], v[150:151]
	v_mul_f32_e32 v93, v93, v93
	v_fmac_f32_e32 v93, v92, v92
	v_mul_f32_e32 v92, v95, v95
	v_fmac_f32_e32 v92, v94, v94
	v_mul_f32_e32 v89, v89, v89
	v_add_f32_e32 v92, v93, v92
	v_fmac_f32_e32 v89, v88, v88
	v_add_f32_e32 v88, v89, v92
	v_mul_f32_e32 v89, v91, v91
	v_fmac_f32_e32 v89, v90, v90
	v_pk_fma_f32 v[84:85], s[12:13], v[84:85], v[148:149]
	v_add_f32_e32 v92, v89, v88
	v_pk_fma_f32 v[88:89], s[12:13], v[80:81], v[144:145]
	v_mul_f32_e32 v80, v85, v85
	v_mul_f32_e32 v81, v87, v87
	v_fmac_f32_e32 v80, v84, v84
	v_fmac_f32_e32 v81, v86, v86
	v_add_f32_e32 v80, v80, v81
	v_mul_f32_e32 v81, v89, v89
	v_cvt_pk_bf16_f32 v101, v90, v91
	v_pk_fma_f32 v[90:91], s[48:49], v[82:83], v[146:147]
	v_fmac_f32_e32 v81, v88, v88
	v_add_f32_e32 v80, v81, v80
	v_mul_f32_e32 v81, v91, v91
	v_fmac_f32_e32 v81, v90, v90
	v_add_f32_e32 v80, v81, v80
	v_add_f32_e32 v80, v92, v80
	ds_bpermute_b32 v81, v114, v80
	v_readlane_b32 s50, v250, 42
	v_readlane_b32 s51, v250, 43
	v_readlane_b32 s65, v250, 1
	v_readlane_b32 s66, v250, 2
	s_waitcnt lgkmcnt(0)
	v_add_f32_e32 v80, v80, v81
	ds_bpermute_b32 v81, v115, v80
	v_lshl_add_u64 v[102:103], v[102:103], 1, s[50:51]
	v_lshl_add_u64 v[102:103], v[196:197], 1, v[102:103]
	v_readlane_b32 s67, v250, 3
	v_readlane_b32 s68, v250, 4
	v_readlane_b32 s69, v250, 5
	global_store_dwordx4 v[102:103], v[98:101], off
	global_store_dwordx4 v[104:105], v[84:87], off offset:512
	global_store_dwordx4 v[104:105], v[88:91], off offset:528
	v_cvt_pk_bf16_f32 v82, v84, v85
	v_cvt_pk_bf16_f32 v83, v86, v87
	s_nop 0
	v_cvt_pk_bf16_f32 v84, v88, v89
	v_cvt_pk_bf16_f32 v85, v90, v91
	global_store_dwordx4 v[102:103], v[82:85], off offset:256
	s_and_saveexec_b64 s[50:51], s[6:7]
	s_cbranch_execz .LBB0_1019
	s_lshl_b32 s53, s52, 2
	s_add_i32 s53, s53, 0
	v_lshl_add_u32 v82, v96, 4, s53
	v_add_u32_e32 v82, 0x20000, v82
	s_waitcnt lgkmcnt(0)
	v_add_f32_e32 v80, v80, v81
	ds_write_b32 v82, v80
.LBB0_1019:
	s_or_b64 exec, exec, s[50:51]
	s_mov_b64 s[98:99], 0xa0000
	v_lshl_add_u64 v[240:241], v[200:201], 0, s[98:99]
	global_load_dwordx4 v[156:159], v[240:241], off
	global_load_dwordx4 v[152:155], v[240:241], off offset:16
	global_load_dwordx4 v[148:151], v[240:241], off offset:512
	global_load_dwordx4 v[144:147], v[240:241], off offset:528
	v_or_b32_e32 v80, 48, v198
	s_waitcnt lgkmcnt(0)
	v_ashrrev_i32_e32 v81, 31, v80
	v_lshlrev_b64 v[82:83], 10, v[80:81]
	v_readlane_b32 s64, v250, 0
	v_lshl_add_u64 v[86:87], v[82:83], 0, s[36:37]
	v_readlane_b32 s70, v250, 6
	v_readlane_b32 s71, v250, 7
	v_pk_fma_f32 v[78:79], s[48:49], v[78:79], v[142:143]
	v_pk_fma_f32 v[76:77], s[12:13], v[76:77], v[140:141]
	v_lshl_add_u64 v[82:83], v[86:87], 2, s[70:71]
	v_lshl_add_u64 v[88:89], v[196:197], 2, v[82:83]
	v_pk_fma_f32 v[74:75], s[48:49], v[74:75], v[138:139]
	v_pk_fma_f32 v[72:73], s[12:13], v[72:73], v[136:137]
	global_store_dwordx4 v[88:89], v[76:79], off
	global_store_dwordx4 v[88:89], v[72:75], off offset:16
	v_cvt_pk_bf16_f32 v82, v76, v77
	v_cvt_pk_bf16_f32 v83, v78, v79
	v_cvt_pk_bf16_f32 v84, v72, v73
	v_pk_fma_f32 v[70:71], s[48:49], v[70:71], v[134:135]
	v_mul_f32_e32 v77, v77, v77
	v_fmac_f32_e32 v77, v76, v76
	v_mul_f32_e32 v76, v79, v79
	v_fmac_f32_e32 v76, v78, v78
	v_mul_f32_e32 v73, v73, v73
	v_add_f32_e32 v76, v77, v76
	v_fmac_f32_e32 v73, v72, v72
	v_add_f32_e32 v72, v73, v76
	v_mul_f32_e32 v73, v75, v75
	v_fmac_f32_e32 v73, v74, v74
	v_pk_fma_f32 v[68:69], s[12:13], v[68:69], v[132:133]
	v_add_f32_e32 v76, v73, v72
	v_pk_fma_f32 v[72:73], s[12:13], v[64:65], v[128:129]
	v_mul_f32_e32 v64, v69, v69
	v_mul_f32_e32 v65, v71, v71
	v_fmac_f32_e32 v64, v68, v68
	v_fmac_f32_e32 v65, v70, v70
	v_add_f32_e32 v64, v64, v65
	v_mul_f32_e32 v65, v73, v73
	v_cvt_pk_bf16_f32 v85, v74, v75
	v_pk_fma_f32 v[74:75], s[48:49], v[66:67], v[130:131]
	v_fmac_f32_e32 v65, v72, v72
	v_add_f32_e32 v64, v65, v64
	v_mul_f32_e32 v65, v75, v75
	v_fmac_f32_e32 v65, v74, v74
	v_add_f32_e32 v64, v65, v64
	v_add_f32_e32 v64, v76, v64
	ds_bpermute_b32 v65, v114, v64
	v_readlane_b32 s50, v250, 42
	v_readlane_b32 s51, v250, 43
	v_readlane_b32 s65, v250, 1
	v_readlane_b32 s66, v250, 2
	s_waitcnt lgkmcnt(0)
	v_add_f32_e32 v64, v64, v65
	ds_bpermute_b32 v65, v115, v64
	v_lshl_add_u64 v[86:87], v[86:87], 1, s[50:51]
	v_lshl_add_u64 v[86:87], v[196:197], 1, v[86:87]
	v_readlane_b32 s67, v250, 3
	v_readlane_b32 s68, v250, 4
	v_readlane_b32 s69, v250, 5
	global_store_dwordx4 v[86:87], v[82:85], off
	global_store_dwordx4 v[88:89], v[68:71], off offset:512
	global_store_dwordx4 v[88:89], v[72:75], off offset:528
	v_cvt_pk_bf16_f32 v66, v68, v69
	v_cvt_pk_bf16_f32 v67, v70, v71
	s_nop 0
	v_cvt_pk_bf16_f32 v68, v72, v73
	v_cvt_pk_bf16_f32 v69, v74, v75
	global_store_dwordx4 v[86:87], v[66:69], off offset:256
	s_and_saveexec_b64 s[50:51], s[6:7]
	s_cbranch_execz .LBB0_1021
	s_lshl_b32 s53, s52, 2
	s_add_i32 s53, s53, 0
	v_lshl_add_u32 v66, v80, 4, s53
	v_add_u32_e32 v66, 0x20000, v66
	s_waitcnt lgkmcnt(0)
	v_add_f32_e32 v64, v64, v65
	ds_write_b32 v66, v64
.LBB0_1021:
	s_or_b64 exec, exec, s[50:51]
	v_add_co_u32_e32 v64, vcc, 0x80000, v200
	s_mov_b64 s[50:51], 0x80000
	s_waitcnt lgkmcnt(0)
	v_addc_co_u32_e32 v65, vcc, 0, v201, vcc
	v_lshl_add_u64 v[66:67], v[200:201], 0, s[50:51]
	s_mov_b64 s[50:51], 0x80200
	v_lshl_add_u64 v[64:65], v[200:201], 0, s[50:51]
	s_mov_b64 s[50:51], 0x90000
	v_add_co_u32_e32 v74, vcc, 0x90000, v200
	v_lshl_add_u64 v[64:65], v[200:201], 0, s[50:51]
	s_mov_b64 s[50:51], 0x90200
	v_addc_co_u32_e32 v75, vcc, 0, v201, vcc
	v_lshl_add_u64 v[66:67], v[200:201], 0, s[50:51]
	s_mov_b64 s[50:51], 0xa0000
	v_add_co_u32_e32 v76, vcc, 0xa0000, v200
	v_lshl_add_u64 v[68:69], v[200:201], 0, s[50:51]
	s_mov_b64 s[50:51], 0xa0200
	v_addc_co_u32_e32 v77, vcc, 0, v201, vcc
	v_lshl_add_u64 v[70:71], v[200:201], 0, s[50:51]
	s_mov_b64 s[50:51], 0xb0000
	v_add_co_u32_e32 v64, vcc, 0xb0000, v200
	v_lshl_add_u64 v[72:73], v[200:201], 0, s[50:51]
	s_mov_b64 s[50:51], 0xb0200
	v_addc_co_u32_e32 v65, vcc, 0, v201, vcc
	v_lshl_add_u64 v[112:113], v[200:201], 0, s[50:51]
	s_nop 0
	global_load_dwordx4 v[76:79], v[64:65], off
	s_nop 0
	global_load_dwordx4 v[72:75], v[72:73], off offset:16
	s_nop 0
	global_load_dwordx4 v[68:71], v[64:65], off offset:512
	s_nop 0
	global_load_dwordx4 v[64:67], v[112:113], off offset:16
	v_add_u32_e32 v112, 0x80, v198
	v_ashrrev_i32_e32 v113, 31, v112
	v_lshlrev_b64 v[132:133], 10, v[112:113]
	v_readlane_b32 s64, v250, 0
	v_lshl_add_u64 v[132:133], v[132:133], 0, s[36:37]
	v_readlane_b32 s70, v250, 6
	v_readlane_b32 s71, v250, 7
	v_readlane_b32 s50, v250, 42
	v_readlane_b32 s51, v250, 43
	v_lshl_add_u64 v[134:135], v[132:133], 2, s[70:71]
	v_lshl_add_u64 v[134:135], v[196:197], 2, v[134:135]
	v_lshl_add_u64 v[132:133], v[132:133], 1, s[50:51]
	v_lshl_add_u64 v[132:133], v[196:197], 1, v[132:133]
	v_readlane_b32 s65, v250, 1
	v_readlane_b32 s66, v250, 2
	v_readlane_b32 s67, v250, 3
	v_readlane_b32 s68, v250, 4
	v_readlane_b32 s69, v250, 5
	s_waitcnt vmcnt(30)
	v_pk_fma_f32 v[58:59], s[48:49], v[58:59], v[224:225]
	v_pk_fma_f32 v[62:63], s[48:49], v[62:63], v[220:221]
	v_pk_fma_f32 v[60:61], s[12:13], v[60:61], v[218:219]
	s_waitcnt vmcnt(30)
	v_pk_fma_f32 v[54:55], s[48:49], v[54:55], v[228:229]
	v_pk_fma_f32 v[52:53], s[12:13], v[52:53], v[226:227]
	v_pk_fma_f32 v[56:57], s[12:13], v[56:57], v[222:223]
	s_waitcnt vmcnt(30)
	v_pk_fma_f32 v[116:117], s[12:13], v[48:49], v[230:231]
	global_store_dwordx4 v[134:135], v[60:63], off
	global_store_dwordx4 v[134:135], v[56:59], off offset:16
	v_cvt_pk_bf16_f32 v48, v60, v61
	v_cvt_pk_bf16_f32 v49, v62, v63
	v_mul_f32_e32 v113, v53, v53
	v_mul_f32_e32 v61, v61, v61
	v_mul_f32_e32 v63, v63, v63
	v_mul_f32_e32 v120, v55, v55
	v_pk_fma_f32 v[118:119], s[48:49], v[50:51], v[232:233]
	v_cvt_pk_bf16_f32 v50, v56, v57
	v_cvt_pk_bf16_f32 v51, v58, v59
	v_mul_f32_e32 v57, v57, v57
	v_mul_f32_e32 v59, v59, v59
	v_mul_f32_e32 v121, v117, v117
	v_fmac_f32_e32 v61, v60, v60
	v_fmac_f32_e32 v63, v62, v62
	v_fmac_f32_e32 v113, v52, v52
	v_fmac_f32_e32 v120, v54, v54
	v_mul_f32_e32 v122, v119, v119
	v_fmac_f32_e32 v57, v56, v56
	v_fmac_f32_e32 v59, v58, v58
	v_fmac_f32_e32 v121, v116, v116
	v_add_f32_e32 v56, v61, v63
	v_add_f32_e32 v58, v113, v120
	v_fmac_f32_e32 v122, v118, v118
	v_add_f32_e32 v56, v57, v56
	v_add_f32_e32 v57, v121, v58
	v_add_f32_e32 v56, v59, v56
	v_add_f32_e32 v57, v122, v57
	v_add_f32_e32 v56, v56, v57
	ds_bpermute_b32 v57, v114, v56
	global_store_dwordx4 v[132:133], v[48:51], off
	global_store_dwordx4 v[134:135], v[52:55], off offset:512
	global_store_dwordx4 v[134:135], v[116:119], off offset:528
	v_cvt_pk_bf16_f32 v50, v52, v53
	v_cvt_pk_bf16_f32 v51, v54, v55
	s_waitcnt lgkmcnt(0)
	v_add_f32_e32 v48, v56, v57
	ds_bpermute_b32 v49, v115, v48
	v_cvt_pk_bf16_f32 v52, v116, v117
	v_cvt_pk_bf16_f32 v53, v118, v119
	global_store_dwordx4 v[132:133], v[50:53], off offset:256
	s_and_saveexec_b64 s[50:51], s[6:7]
	s_cbranch_execz .LBB0_1023
	s_lshl_b32 s53, s52, 2
	s_add_i32 s53, s53, 0
	v_lshl_add_u32 v50, v112, 4, s53
	v_add_u32_e32 v50, 0x20000, v50
	s_waitcnt lgkmcnt(0)
	v_add_f32_e32 v48, v48, v49
	ds_write_b32 v50, v48
.LBB0_1023:
	s_or_b64 exec, exec, s[50:51]
	v_add_u32_e32 v48, 0x90, v198
	s_waitcnt lgkmcnt(0)
	v_ashrrev_i32_e32 v49, 31, v48
	v_lshlrev_b64 v[50:51], 10, v[48:49]
	v_readlane_b32 s64, v250, 0
	v_lshl_add_u64 v[54:55], v[50:51], 0, s[36:37]
	v_readlane_b32 s70, v250, 6
	v_readlane_b32 s71, v250, 7
	s_waitcnt vmcnt(26)
	v_pk_fma_f32 v[46:47], s[48:49], v[46:47], v[174:175]
	v_pk_fma_f32 v[44:45], s[12:13], v[44:45], v[172:173]
	v_lshl_add_u64 v[50:51], v[54:55], 2, s[70:71]
	v_lshl_add_u64 v[56:57], v[196:197], 2, v[50:51]
	s_waitcnt vmcnt(26)
	v_pk_fma_f32 v[42:43], s[48:49], v[42:43], v[170:171]
	v_pk_fma_f32 v[40:41], s[12:13], v[40:41], v[168:169]
	global_store_dwordx4 v[56:57], v[44:47], off
	global_store_dwordx4 v[56:57], v[40:43], off offset:16
	v_cvt_pk_bf16_f32 v50, v44, v45
	v_cvt_pk_bf16_f32 v51, v46, v47
	v_cvt_pk_bf16_f32 v52, v40, v41
	s_waitcnt vmcnt(28)
	v_pk_fma_f32 v[38:39], s[48:49], v[38:39], v[166:167]
	v_mul_f32_e32 v45, v45, v45
	v_fmac_f32_e32 v45, v44, v44
	v_mul_f32_e32 v44, v47, v47
	v_fmac_f32_e32 v44, v46, v46
	v_mul_f32_e32 v41, v41, v41
	v_add_f32_e32 v44, v45, v44
	v_fmac_f32_e32 v41, v40, v40
	v_add_f32_e32 v40, v41, v44
	v_mul_f32_e32 v41, v43, v43
	v_fmac_f32_e32 v41, v42, v42
	v_pk_fma_f32 v[36:37], s[12:13], v[36:37], v[164:165]
	v_add_f32_e32 v44, v41, v40
	s_waitcnt vmcnt(28)
	v_pk_fma_f32 v[40:41], s[12:13], v[32:33], v[160:161]
	v_mul_f32_e32 v32, v37, v37
	v_mul_f32_e32 v33, v39, v39
	v_fmac_f32_e32 v32, v36, v36
	v_fmac_f32_e32 v33, v38, v38
	v_add_f32_e32 v32, v32, v33
	v_mul_f32_e32 v33, v41, v41
	v_cvt_pk_bf16_f32 v53, v42, v43
	v_pk_fma_f32 v[42:43], s[48:49], v[34:35], v[162:163]
	v_fmac_f32_e32 v33, v40, v40
	v_add_f32_e32 v32, v33, v32
	v_mul_f32_e32 v33, v43, v43
	v_fmac_f32_e32 v33, v42, v42
	v_add_f32_e32 v32, v33, v32
	v_add_f32_e32 v32, v44, v32
	ds_bpermute_b32 v33, v114, v32
	v_readlane_b32 s50, v250, 42
	v_readlane_b32 s51, v250, 43
	v_readlane_b32 s65, v250, 1
	v_readlane_b32 s66, v250, 2
	s_waitcnt lgkmcnt(0)
	v_add_f32_e32 v32, v32, v33
	ds_bpermute_b32 v33, v115, v32
	v_lshl_add_u64 v[54:55], v[54:55], 1, s[50:51]
	v_lshl_add_u64 v[54:55], v[196:197], 1, v[54:55]
	v_readlane_b32 s67, v250, 3
	v_readlane_b32 s68, v250, 4
	v_readlane_b32 s69, v250, 5
	global_store_dwordx4 v[54:55], v[50:53], off
	global_store_dwordx4 v[56:57], v[36:39], off offset:512
	global_store_dwordx4 v[56:57], v[40:43], off offset:528
	v_cvt_pk_bf16_f32 v34, v36, v37
	v_cvt_pk_bf16_f32 v35, v38, v39
	s_nop 0
	v_cvt_pk_bf16_f32 v36, v40, v41
	v_cvt_pk_bf16_f32 v37, v42, v43
	global_store_dwordx4 v[54:55], v[34:37], off offset:256
	s_and_saveexec_b64 s[50:51], s[6:7]
	s_cbranch_execz .LBB0_1025
	s_lshl_b32 s53, s52, 2
	s_add_i32 s53, s53, 0
	v_lshl_add_u32 v34, v48, 4, s53
	v_add_u32_e32 v34, 0x20000, v34
	s_waitcnt lgkmcnt(0)
	v_add_f32_e32 v32, v32, v33
	ds_write_b32 v34, v32
.LBB0_1025:
	s_or_b64 exec, exec, s[50:51]
	v_add_u32_e32 v32, 0xa0, v198
	s_waitcnt lgkmcnt(0)
	v_ashrrev_i32_e32 v33, 31, v32
	v_lshlrev_b64 v[34:35], 10, v[32:33]
	v_readlane_b32 s64, v250, 0
	v_lshl_add_u64 v[38:39], v[34:35], 0, s[36:37]
	v_readlane_b32 s70, v250, 6
	v_readlane_b32 s71, v250, 7
	s_waitcnt vmcnt(22)
	v_pk_fma_f32 v[30:31], s[48:49], v[30:31], v[158:159]
	v_pk_fma_f32 v[28:29], s[12:13], v[28:29], v[156:157]
	v_lshl_add_u64 v[34:35], v[38:39], 2, s[70:71]
	v_lshl_add_u64 v[40:41], v[196:197], 2, v[34:35]
	s_waitcnt vmcnt(22)
	v_pk_fma_f32 v[26:27], s[48:49], v[26:27], v[154:155]
	v_pk_fma_f32 v[24:25], s[12:13], v[24:25], v[152:153]
	global_store_dwordx4 v[40:41], v[28:31], off
	global_store_dwordx4 v[40:41], v[24:27], off offset:16
	v_cvt_pk_bf16_f32 v34, v28, v29
	v_cvt_pk_bf16_f32 v35, v30, v31
	v_cvt_pk_bf16_f32 v36, v24, v25
	s_waitcnt vmcnt(24)
	v_pk_fma_f32 v[22:23], s[48:49], v[22:23], v[150:151]
	v_mul_f32_e32 v29, v29, v29
	v_fmac_f32_e32 v29, v28, v28
	v_mul_f32_e32 v28, v31, v31
	v_fmac_f32_e32 v28, v30, v30
	v_mul_f32_e32 v25, v25, v25
	v_add_f32_e32 v28, v29, v28
	v_fmac_f32_e32 v25, v24, v24
	v_add_f32_e32 v24, v25, v28
	v_mul_f32_e32 v25, v27, v27
	v_fmac_f32_e32 v25, v26, v26
	v_pk_fma_f32 v[20:21], s[12:13], v[20:21], v[148:149]
	v_add_f32_e32 v28, v25, v24
	s_waitcnt vmcnt(24)
	v_pk_fma_f32 v[24:25], s[12:13], v[16:17], v[144:145]
	v_mul_f32_e32 v16, v21, v21
	v_mul_f32_e32 v17, v23, v23
	v_fmac_f32_e32 v16, v20, v20
	v_fmac_f32_e32 v17, v22, v22
	v_add_f32_e32 v16, v16, v17
	v_mul_f32_e32 v17, v25, v25
	v_cvt_pk_bf16_f32 v37, v26, v27
	v_pk_fma_f32 v[26:27], s[48:49], v[18:19], v[146:147]
	v_fmac_f32_e32 v17, v24, v24
	v_add_f32_e32 v16, v17, v16
	v_mul_f32_e32 v17, v27, v27
	v_fmac_f32_e32 v17, v26, v26
	v_add_f32_e32 v16, v17, v16
	v_add_f32_e32 v16, v28, v16
	ds_bpermute_b32 v17, v114, v16
	v_readlane_b32 s50, v250, 42
	v_readlane_b32 s51, v250, 43
	v_readlane_b32 s65, v250, 1
	v_readlane_b32 s66, v250, 2
	s_waitcnt lgkmcnt(0)
	v_add_f32_e32 v16, v16, v17
	ds_bpermute_b32 v17, v115, v16
	v_lshl_add_u64 v[38:39], v[38:39], 1, s[50:51]
	v_lshl_add_u64 v[38:39], v[196:197], 1, v[38:39]
	v_readlane_b32 s67, v250, 3
	v_readlane_b32 s68, v250, 4
	v_readlane_b32 s69, v250, 5
	global_store_dwordx4 v[38:39], v[34:37], off
	global_store_dwordx4 v[40:41], v[20:23], off offset:512
	global_store_dwordx4 v[40:41], v[24:27], off offset:528
	v_cvt_pk_bf16_f32 v18, v20, v21
	v_cvt_pk_bf16_f32 v19, v22, v23
	s_nop 0
	v_cvt_pk_bf16_f32 v20, v24, v25
	v_cvt_pk_bf16_f32 v21, v26, v27
	global_store_dwordx4 v[38:39], v[18:21], off offset:256
	s_and_saveexec_b64 s[50:51], s[6:7]
	s_cbranch_execz .LBB0_1027
	s_lshl_b32 s53, s52, 2
	s_add_i32 s53, s53, 0
	v_lshl_add_u32 v18, v32, 4, s53
	v_add_u32_e32 v18, 0x20000, v18
	s_waitcnt lgkmcnt(0)
	v_add_f32_e32 v16, v16, v17
	ds_write_b32 v18, v16
